# up-GEMM phase: WGs with odd m_local start ~5us later (s_sleep) so tile epilogues of one half overlap K-loops of the other half
# baseline (speedup 1.0000x reference)
.LBB0_2068:
	s_or_b64 exec, exec, s[0:1]
	s_mov_b64 s[30:31], s[90:91]
	s_waitcnt lgkmcnt(0)
	s_barrier
	s_bitcmp1_b32 s94, 3
	s_cbranch_scc0 .Lp8_nostagger
	s_sleep 100
	s_sleep 100
.Lp8_nostagger:
	s_cmp_eq_u64 s[30:31], 0
	s_cbranch_scc1 .LBB0_2120
	s_load_dwordx4 s[60:63], s[30:31], 0xa0
	s_load_dwordx2 s[16:17], s[30:31], 0xd0
	s_add_i32 s7, s92, s94
	v_mov_b32_e32 v4, v252
	s_waitcnt lgkmcnt(0)
	s_add_u32 s34, s60, 0x5400
	s_addc_u32 s35, s61, 0
	s_add_u32 s36, s60, 0xa800
	s_addc_u32 s37, s61, 0
	s_add_u32 s58, s60, 0x2a00
	s_addc_u32 s59, s61, 0
	s_add_u32 s64, s60, 0x7e00
	s_addc_u32 s65, s61, 0
	s_add_u32 s66, s60, 0xd200
	s_addc_u32 s67, s61, 0
	s_cmpk_gt_i32 s94, 0xad3
	v_readfirstlane_b32 s0, v4
	s_cbranch_scc1 .LBB0_2085
	v_bfe_i32 v1, v4, 27, 1
	v_lshlrev_b32_e32 v0, 4, v4
	v_lshrrev_b32_e32 v1, 22, v1
	v_add_u32_e32 v1, v0, v1
	s_add_u32 s24, s16, 0x10d70200
	v_and_b32_e32 v1, 0xfffffc00, v1
	v_writelane_b32 v254, s95, 32
	s_addc_u32 s25, s17, 0
	v_sub_u32_e32 v0, v0, v1
	v_writelane_b32 v254, s93, 36
	s_add_u32 s26, s16, 0x1840000
	v_lshrrev_b32_e32 v1, 4, v0
	v_ashrrev_i32_e32 v3, 31, v4
	s_addc_u32 s27, s17, 0
	s_ashr_i32 s1, s0, 6
	v_writelane_b32 v254, s0, 44
	s_ashr_i32 s23, s0, 8
	s_mul_i32 s0, s78, 0x15a
	v_bitop3_b32 v0, v1, v0, 32 bitop3:0x6c
	v_lshrrev_b32_e32 v3, 26, v3
	s_lshl_b32 s28, s1, 10
	s_add_i32 s0, s0, 4
	v_ashrrev_i32_e32 v1, 31, v0
	v_add_u32_e32 v3, v4, v3
	s_cmp_lt_i32 s78, 4
	s_mul_i32 s2, s78, 0x15b
	v_lshrrev_b32_e32 v1, 26, v1
	v_ashrrev_i32_e32 v3, 6, v3
	v_add_u32_e32 v1, v0, v1
	v_lshlrev_b32_e32 v5, 3, v3
	s_cselect_b32 s0, s2, s0
	v_readlane_b32 s2, v254, 2
	v_ashrrev_i32_e32 v2, 6, v1
	v_and_b32_e32 v5, -16, v5
	s_add_i32 s0, s0, s2
	v_add_u32_e32 v5, v2, v5
	v_and_b32_e32 v6, 3, v2
	s_mov_b32 s3, 0x3fffe0
	s_mul_hi_i32 s2, s0, 0x30c30c31
	v_and_or_b32 v6, v5, s3, v6
	v_and_b32_e32 v1, 0xc0, v1
	s_lshr_b32 s3, s2, 31
	s_ashr_i32 s2, s2, 5
	v_sub_u32_e32 v0, v0, v1
	v_mov_b32_e32 v1, 1
	s_add_i32 s2, s2, s3
	v_lshlrev_b32_e32 v3, 5, v3
	v_ashrrev_i16_sdwa v0, v1, sext(v0) dst_sel:DWORD dst_unused:UNUSED_PAD src0_sel:DWORD src1_sel:BYTE_0
	s_lshl_b32 s4, s2, 3
	v_and_b32_e32 v3, 32, v3
	v_bfe_i32 v0, v0, 0, 16
	v_lshrrev_b32_e32 v1, 6, v5
	v_lshlrev_b32_e32 v2, 3, v2
	s_sub_i32 s3, 0x84, s4
	v_add_lshl_u32 v0, v3, v0, 1
	v_mul_i32_i24_e32 v1, 0x7e, v1
	v_and_b32_e32 v2, 0x78, v2
	v_bfe_u32 v3, v5, 4, 2
	s_min_u32 s5, s3, 8
	s_mulk_i32 s2, 0xa8
	v_add3_u32 v1, v1, v2, v3
	s_sub_i32 s6, s0, s2
	v_cvt_f32_ubyte0_e32 v3, s5
	v_lshrrev_b32_e32 v7, 2, v5
	v_lshlrev_b32_e32 v8, 1, v5
	v_cvt_f32_i32_e32 v2, s6
	v_rcp_iflag_f32_e32 v5, v3
	v_and_b32_e32 v7, 4, v7
	v_and_b32_e32 v8, 24, v8
	v_or3_b32 v6, v6, v7, v8
	v_lshl_add_u32 v128, v6, 10, v0
	v_lshl_add_u32 v130, v1, 10, v0
	v_mul_f32_e32 v0, v2, v5
	v_trunc_f32_e32 v0, v0
	v_fma_f32 v1, -v0, v3, v2
	v_cvt_i32_f32_e32 v0, v0
	s_ashr_i32 s0, s6, 30
	s_or_b32 s0, s0, 1
	v_cmp_ge_f32_e64 s[2:3], |v1|, v3
	s_and_b64 s[2:3], s[2:3], exec
	s_cselect_b32 s0, s0, 0
	v_readfirstlane_b32 s2, v0
	s_add_i32 s0, s2, s0
	s_mul_i32 s2, s0, s5
	s_sub_i32 s2, s6, s2
	s_sext_i32_i16 s2, s2
	s_add_i32 s9, s4, s2
	s_mul_hi_i32 s2, s9, 0x3e0f83e1
	s_lshr_b32 s3, s2, 31
	s_ashr_i32 s2, s2, 3
	s_add_i32 s2, s2, s3
	s_mul_i32 s3, s2, 0xffffffdf
	s_add_i32 s4, s3, s9
	s_ashr_i32 s3, s2, 31
	s_mulk_i32 s4, 0xfc
	s_lshl_b64 s[2:3], s[2:3], 13
	s_ashr_i32 s5, s4, 31
	s_add_u32 s2, s2, s4
	s_addc_u32 s3, s3, s5
	s_lshl_b64 s[2:3], s[2:3], 10
	s_add_u32 s2, s24, s2
	s_addc_u32 s3, s25, s3
	s_add_u32 s20, s2, 0xfffff800
	s_addc_u32 s21, s3, -1
	s_bfe_i64 s[2:3], s[0:1], 0x100000
	s_lshl_b64 s[2:3], s[2:3], 18
	s_add_u32 s18, s26, s2
	s_addc_u32 s19, s27, s3
	v_mov_b32_e32 v129, 0
	s_add_i32 s29, s28, 0
	v_lshl_add_u64 v[0:1], s[18:19], 0, v[128:129]
	s_add_i32 m0, s29, 0x10000
	s_mov_b64 s[2:3], 0x10000
	global_load_lds_dwordx4 v128, s[18:19]
	v_lshl_add_u64 v[2:3], v[0:1], 0, s[2:3]
	s_add_i32 m0, s29, 0x12000
	v_mov_b32_e32 v131, v129
	global_load_lds_dwordx4 v[2:3], off
	v_lshl_add_u64 v[2:3], s[20:21], 0, v[130:131]
	s_mov_b32 m0, s29
	s_mov_b64 s[2:3], 0x1f800
	s_add_i32 s33, s29, 0x2000
	global_load_lds_dwordx4 v130, s[20:21]
	v_lshl_add_u64 v[6:7], v[2:3], 0, s[2:3]
	s_mov_b32 m0, s33
	s_mov_b64 s[2:3], 0x20000
	global_load_lds_dwordx4 v[6:7], off
	v_lshl_add_u64 v[6:7], v[0:1], 0, s[2:3]
	s_add_i32 m0, s29, 0x14000
	s_mov_b64 s[2:3], 0x30000
	global_load_lds_dwordx4 v[6:7], off
	v_lshl_add_u64 v[6:7], v[0:1], 0, s[2:3]
	s_add_i32 m0, s29, 0x16000
	s_mov_b64 s[12:13], 0x1000
	s_add_i32 s39, s29, 0x4000
	global_load_lds_dwordx4 v[6:7], off
	v_lshl_add_u64 v[6:7], v[2:3], 0, s[12:13]
	s_mov_b32 m0, s39
	s_mov_b64 s[68:69], 0x20800
	s_add_i32 s88, s29, 0x6000
	global_load_lds_dwordx4 v[6:7], off
	v_lshl_add_u64 v[6:7], v[2:3], 0, s[68:69]
	s_mov_b32 m0, s88
	s_mov_b32 s10, s92
	global_load_lds_dwordx4 v[6:7], off
	s_cmp_lg_u32 s23, 1
	s_movk_i32 s89, 0x2000
	s_cbranch_scc1 .LBB0_2072
	s_barrier
